# A-attention main loop hand software-pipelined: QK(next) MFMAs interleaved with exp/cvt of current tile, K staged one tile ahead, early LDS writes
# speedup vs baseline: 1.0193x; 1.0193x over previous
; #define LAS __attribute__((address_space(3)))
; template <bool TRACK> ...
;     ...
;     { const int tl = 0 < n0 ? 0 : t1lo; kreg = *(const u32x4*)(Kb + (size_t)(tl * 64 + srow) * 64 + sc * 8); vreg = *(const u32x4*)(Vtb + (size_t)srow * KEYS + tl * 64 + sc * 8); }
;     bf16x8 qf[4];
;     { const int qrow = wave * 32 + r32; const bf16* qp = Qraw + (size_t)qrow * INW + hi * 8;
;       float qv[4][8]; float ss = 0.f;
; #pragma unroll
;       for (int d = 0; d < 4; ++d) { unpack8(*(const u32x4*)(qp + d * 16), qv[d]);
; #pragma unroll
;           for (int e = 0; e < 8; ++e) ss += qv[d][e] * qv[d][e]; }
;       ss += __shfl_xor(ss, 32);
;       const float rs = rsqrtf(ss * (1.0f / 64.0f) + 1e-6f) * (0.125f * LOG2E);
; #pragma unroll
;       for (int d = 0; d < 4; ++d) { const f32x4 w0 = *(const f32x4*)(qnw + d * 16 + hi * 8), w1 = *(const f32x4*)(qnw + d * 16 + hi * 8 + 4);
;           qv[d][0] *= rs * w0.x; qv[d][1] *= rs * w0.y; qv[d][2] *= rs * w0.z; qv[d][3] *= rs * w0.w; qv[d][4] *= rs * w1.x; qv[d][5] *= rs * w1.y; qv[d][6] *= rs * w1.z; qv[d][7] *= rs * w1.w; }
;       if (tpos0 >= 0) { const float* cp = ropet + (size_t)(tpos0 + qrow) * 32 + hi * 8; const float* sp = cp + 2048 * 32;
; #pragma unroll
;           for (int ax = 0; ax < 2; ++ax) { const f32x4 c0 = *(const f32x4*)(cp + ax * 16), c1 = *(const f32x4*)(cp + ax * 16 + 4), s0_ = *(const f32x4*)(sp + ax * 16), s1_ = *(const f32x4*)(sp + ax * 16 + 4);
;               const float cc[8] = {c0.x, c0.y, c0.z, c0.w, c1.x, c1.y, c1.z, c1.w}, sn[8] = {s0_.x, s0_.y, s0_.z, s0_.w, s1_.x, s1_.y, s1_.z, s1_.w};
; #pragma unroll
;               for (int e = 0; e < 8; ++e) { const float xa = qv[2 * ax][e], xb = qv[2 * ax + 1][e]; qv[2 * ax][e] = xa * cc[e] - xb * sn[e]; qv[2 * ax + 1][e] = xb * cc[e] + xa * sn[e]; } } }
; #pragma unroll
;       for (int d = 0; d < 4; ++d) { u32x4 w; w.x = pk2(qv[d][0], qv[d][1]); w.y = pk2(qv[d][2], qv[d][3]); w.z = pk2(qv[d][4], qv[d][5]); w.w = pk2(qv[d][6], qv[d][7]); qf[d] = __builtin_bit_cast(bf16x8, w); } }
;     __syncthreads();
;     *(LAS u32x4*)(lds + (srow * 72 + sc * 8) * 2) = kreg; { LAS u32x2* vw_ = (LAS u32x2*)(lds + 9216 + (srow * 68 + sc * 8) * 2); vw_[0] = (u32x2){vreg.x, vreg.y}; vw_[1] = (u32x2){vreg.z, vreg.w}; }
;     __syncthreads();
.LBB0_165:
	s_andn2_saveexec_b64 s[48:49], s[48:49]
	s_cbranch_execz .LBB0_169
	ds_bpermute_b32 v19, v188, v18
	s_mov_b32 s4, 0x800000
	s_add_i32 s51, s51, s73
	s_and_b32 s20, s51, 0x1fff
	s_mul_i32 s22, s20, 0x48000
	s_waitcnt lgkmcnt(0)
	v_add_f32_e32 v18, v18, v19
	v_fmamk_f32 v18, v18, 0x3c800000, v163
	v_cmp_gt_f32_e32 vcc, s4, v18
	v_mul_f32_e32 v19, 0x4b800000, v18
	s_add_u32 s20, s50, s22
	v_cndmask_b32_e32 v18, v18, v19, vcc
	v_rsq_f32_e32 v18, v18
	s_addc_u32 s21, 0, 0
	v_mov_b32_e32 v135, v1
	v_readlane_b32 s4, v250, 63
	v_mul_f32_e32 v19, 0x45800000, v18
	v_cndmask_b32_e32 v18, v18, v19, vcc
	v_mul_f32_e32 v70, 0x3e38aa3b, v18
	global_load_dwordx4 v[26:29], v[16:17], off offset:192
	global_load_dwordx4 v[18:21], v[16:17], off offset:144
	global_load_dwordx4 v[30:33], v[16:17], off offset:128
	global_load_dwordx4 v[72:75], v[16:17], off offset:16
	global_load_dwordx4 v[76:79], v[16:17], off
	global_load_dwordx4 v[80:83], v[16:17], off offset:80
	global_load_dwordx4 v[84:87], v[16:17], off offset:64
	global_load_dwordx4 v[88:91], v[22:23], off offset:16
	global_load_dwordx4 v[92:95], v[22:23], off
	global_load_dwordx4 v[96:99], v[14:15], off offset:16
	s_nop 0
	global_load_dwordx4 v[14:17], v[14:15], off
	s_waitcnt vmcnt(11)
	v_pk_mul_f32 v[10:11], v[10:11], v[70:71] op_sel_hi:[1,0]
	v_pk_mul_f32 v[12:13], v[12:13], v[70:71] op_sel_hi:[1,0]
	v_pk_mul_f32 v[40:41], v[10:11], v[40:41]
	v_pk_mul_f32 v[12:13], v[12:13], v[36:37]
	v_readlane_b32 s5, v249, 0
	s_waitcnt vmcnt(10)
	v_pk_mul_f32 v[26:27], v[26:27], v[70:71] op_sel_hi:[1,0]
	s_waitcnt vmcnt(9)
	v_pk_mul_f32 v[10:11], v[18:19], v[70:71] op_sel_hi:[1,0]
	v_pk_mul_f32 v[28:29], v[28:29], v[70:71] op_sel_hi:[1,0]
	v_pk_mul_f32 v[18:19], v[10:11], v[38:39]
	s_waitcnt vmcnt(6)
	v_pk_mul_f32 v[68:69], v[76:77], v[70:71] op_sel_hi:[1,0]
	s_nop 0
	v_pk_mul_f32 v[66:67], v[68:69], v[66:67]
	s_waitcnt vmcnt(4)
	v_pk_mul_f32 v[68:69], v[84:85], v[70:71] op_sel_hi:[1,0]
	s_nop 0
	v_pk_mul_f32 v[68:69], v[68:69], v[64:65]
	s_waitcnt vmcnt(0)
	v_pk_mul_f32 v[64:65], v[14:15], v[68:69]
	v_pk_mul_f32 v[14:15], v[14:15], v[66:67]
	v_pk_fma_f32 v[64:65], v[92:93], v[66:67], v[64:65] neg_lo:[0,0,1] neg_hi:[0,0,1]
	v_pk_fma_f32 v[66:67], v[92:93], v[68:69], v[14:15]
	v_pk_mul_f32 v[14:15], v[78:79], v[70:71] op_sel_hi:[1,0]
	s_nop 0
	v_pk_mul_f32 v[14:15], v[14:15], v[62:63]
	v_pk_mul_f32 v[62:63], v[86:87], v[70:71] op_sel_hi:[1,0]
	s_nop 0
	v_pk_mul_f32 v[62:63], v[62:63], v[60:61]
	s_nop 0
	v_pk_mul_f32 v[60:61], v[16:17], v[62:63]
	s_nop 0
	v_pk_fma_f32 v[60:61], v[94:95], v[14:15], v[60:61] neg_lo:[0,0,1] neg_hi:[0,0,1]
	v_pk_mul_f32 v[14:15], v[16:17], v[14:15]
	v_pk_mul_f32 v[16:17], v[80:81], v[70:71] op_sel_hi:[1,0]
	v_pk_fma_f32 v[62:63], v[94:95], v[62:63], v[14:15]
	v_pk_mul_f32 v[14:15], v[72:73], v[70:71] op_sel_hi:[1,0]
	v_pk_mul_f32 v[16:17], v[16:17], v[56:57]
	v_pk_mul_f32 v[14:15], v[14:15], v[58:59]
	v_pk_mul_f32 v[56:57], v[96:97], v[16:17]
	v_cvt_pk_bf16_f32 v94, v64, v65
	v_pk_fma_f32 v[56:57], v[88:89], v[14:15], v[56:57] neg_lo:[0,0,1] neg_hi:[0,0,1]
	v_pk_mul_f32 v[14:15], v[96:97], v[14:15]
	v_cvt_pk_bf16_f32 v95, v60, v61
	v_pk_fma_f32 v[58:59], v[88:89], v[16:17], v[14:15]
	v_pk_mul_f32 v[16:17], v[82:83], v[70:71] op_sel_hi:[1,0]
	v_pk_mul_f32 v[14:15], v[74:75], v[70:71] op_sel_hi:[1,0]
	v_pk_mul_f32 v[16:17], v[16:17], v[24:25]
	v_pk_mul_f32 v[14:15], v[14:15], v[54:55]
	v_pk_mul_f32 v[24:25], v[98:99], v[16:17]
	v_cvt_pk_bf16_f32 v92, v58, v59
	v_pk_fma_f32 v[54:55], v[90:91], v[14:15], v[24:25] neg_lo:[0,0,1] neg_hi:[0,0,1]
	v_pk_mul_f32 v[14:15], v[98:99], v[14:15]
	v_cvt_pk_bf16_f32 v96, v56, v57
	v_pk_fma_f32 v[68:69], v[90:91], v[16:17], v[14:15]
	global_load_dwordx4 v[14:17], v[22:23], off offset:80
	global_load_dwordx4 v[72:75], v[22:23], off offset:64
	s_nop 0
	global_load_dwordx4 v[22:25], v[42:43], off offset:16
	global_load_dwordx4 v[76:79], v[42:43], off
	v_pk_mul_f32 v[42:43], v[26:27], v[52:53]
	v_pk_mul_f32 v[26:27], v[30:31], v[70:71] op_sel_hi:[1,0]
	s_nop 0
	v_pk_mul_f32 v[30:31], v[26:27], v[50:51]
	s_barrier
	ds_write_b128 v45, v[2:5]
	ds_write2_b64 v71, v[6:7], v[8:9] offset1:1
	v_mov_b32_e32 v45, v1
	v_lshl_add_u64 v[2:3], s[20:21], 0, v[44:45]
	s_add_u32 s20, s45, s22
	v_lshl_add_u64 v[2:3], v[2:3], 0, v[134:135]
	s_addc_u32 s21, 0, 0
	v_lshl_add_u64 v[114:115], s[4:5], 0, v[2:3]
	v_lshl_add_u64 v[2:3], s[20:21], 0, v[134:135]
	v_readlane_b32 s4, v249, 1
	v_lshl_add_u64 v[2:3], v[2:3], 0, v[0:1]
	v_readlane_b32 s5, v249, 2
	s_waitcnt lgkmcnt(0)
	s_barrier
; template <bool TRACK> ...
;     ...
;     __syncthreads();
;     *(LAS u32x4*)(lds + (srow * 72 + sc * 8) * 2) = kreg; { LAS u32x2* vw_ = (LAS u32x2*)(lds + 9216 + (srow * 68 + sc * 8) * 2); vw_[0] = (u32x2){vreg.x, vreg.y}; vw_[1] = (u32x2){vreg.z, vreg.w}; }
;     __syncthreads();
;     f32x16 o0, o1;
; #pragma unroll
;     for (int r = 0; r < 16; ++r) { o0[r] = 0.f; o1[r] = 0.f; }
;     float m = m_init, lsum = hi == 0 ? l_init : 0.f;
;     f32x16 negm, lacc;
; #pragma unroll
;     for (int r = 0; r < 16; ++r) { negm[r] = TRACK ? -m_init : 0.f; lacc[r] = TRACK ? 0.f : l_init * __builtin_amdgcn_exp2f(m_init); }
;     const bf16x8 ones = __builtin_bit_cast(bf16x8, ((u32x4){0x3f803f80u, 0x3f803f80u, 0x3f803f80u, 0x3f803f80u}));
;     for (int j = 0; j < nt; ++j) {
;         const int cur = j & 1; const int tl = j < n0 ? j : t1lo + (j - n0);
;         if (j + 1 < nt) { const int tn = (j + 1) < n0 ? (j + 1) : t1lo + (j + 1 - n0);
;             kreg = *(const u32x4*)(Kb + (size_t)(tn * 64 + srow) * 64 + sc * 8); vreg = *(const u32x4*)(Vtb + (size_t)srow * KEYS + tn * 64 + sc * 8); }
;         bool active = true; bool mt = masked && j >= n0; const int kpos0 = (tl - 4) * 64;
;         if (mt) { const int qs = qstart + wave * 32; active = !(kpos0 > qs + 31 + 128 || kpos0 + 63 < qs - 128);
;             if (kpos0 >= qs + 31 - 128 && kpos0 + 63 <= qs + 128) mt = false; }
;         if (active) {
;             const LAS unsigned char* Kbuf = lds + cur * 18432; const LAS unsigned char* Vbuf = Kbuf + 9216;
;             f32x16 s0 = negm, s1 = negm;
;             u32x2 vq[8];
;             if constexpr (!TRACK) {
;             bf16x8 kf[8];
; #pragma unroll
;             for (int d = 0; d < 4; ++d) { kf[2 * d] = *(const LAS bf16x8*)(Kbuf + (r32 * 72 + d * 16 + hi * 8) * 2); kf[2 * d + 1] = *(const LAS bf16x8*)(Kbuf + ((32 + r32) * 72 + d * 16 + hi * 8) * 2); }
;             __builtin_amdgcn_sched_barrier(0);
; #pragma unroll
;             for (int d = 0; d < 4; ++d) {
;                 s0 = __builtin_amdgcn_mfma_f32_32x32x16_bf16(kf[2 * d], qf[d], s0, 0, 0, 0);
;                 s1 = __builtin_amdgcn_mfma_f32_32x32x16_bf16(kf[2 * d + 1], qf[d], s1, 0, 0, 0);
;             }
;     ...
;             for (int r = 0; r < 16; ++r) { s0[r] = __builtin_amdgcn_exp2f(s0[r]); s1[r] = __builtin_amdgcn_exp2f(s1[r]); }
;             }
;             bf16x8 pk[4];
;             { u32x4 w;
	v_lshl_add_u64 v[116:117], s[4:5], 0, v[2:3]
	global_load_dwordx4 v[230:233], v[114:115], off
	v_mov_b32_e32 v2, 0
	v_cvt_pk_bf16_f32 v90, v66, v67
	v_cvt_pk_bf16_f32 v91, v62, v63
	v_cvt_pk_bf16_f32 v93, v68, v69
	v_cvt_pk_bf16_f32 v97, v54, v55
	s_mov_b32 s20, 0
	v_mov_b32_e32 v3, v2
	v_mov_b32_e32 v4, v2
	v_mov_b32_e32 v5, v2
	v_mov_b32_e32 v6, v2
	v_mov_b32_e32 v7, v2
	v_mov_b32_e32 v8, v2
	v_mov_b32_e32 v9, v2
	v_mov_b32_e32 v36, v2
	v_mov_b32_e32 v37, v2
	v_mov_b32_e32 v38, v2
	v_mov_b32_e32 v39, v2
	v_mov_b32_e32 v44, v2
	v_mov_b32_e32 v45, v2
	s_mov_b64 s[4:5], 0x2000
	s_waitcnt vmcnt(2)
	v_pk_mul_f32 v[10:11], v[40:41], v[22:23]
	s_waitcnt vmcnt(1)
	v_pk_mul_f32 v[26:27], v[42:43], v[76:77]
	v_pk_fma_f32 v[10:11], v[18:19], v[14:15], v[10:11] neg_lo:[0,0,1] neg_hi:[0,0,1]
	v_pk_fma_f32 v[26:27], v[30:31], v[72:73], v[26:27] neg_lo:[0,0,1] neg_hi:[0,0,1]
	v_pk_mul_f32 v[30:31], v[30:31], v[76:77]
	v_pk_mul_f32 v[18:19], v[18:19], v[22:23]
	v_pk_fma_f32 v[30:31], v[42:43], v[72:73], v[30:31]
	v_pk_mul_f32 v[42:43], v[28:29], v[48:49]
	v_pk_mul_f32 v[28:29], v[32:33], v[70:71] op_sel_hi:[1,0]
	v_pk_fma_f32 v[14:15], v[40:41], v[14:15], v[18:19]
	v_pk_mul_f32 v[18:19], v[20:21], v[70:71] op_sel_hi:[1,0]
	v_pk_mul_f32 v[32:33], v[28:29], v[46:47]
	v_pk_mul_f32 v[28:29], v[42:43], v[78:79]
	v_pk_mul_f32 v[18:19], v[18:19], v[34:35]
	v_pk_mul_f32 v[20:21], v[12:13], v[24:25]
	v_pk_fma_f32 v[28:29], v[32:33], v[74:75], v[28:29] neg_lo:[0,0,1] neg_hi:[0,0,1]
	v_pk_mul_f32 v[32:33], v[32:33], v[78:79]
	v_pk_fma_f32 v[20:21], v[18:19], v[16:17], v[20:21] neg_lo:[0,0,1] neg_hi:[0,0,1]
	v_pk_mul_f32 v[18:19], v[18:19], v[24:25]
	v_pk_fma_f32 v[32:33], v[42:43], v[74:75], v[32:33]
	v_pk_fma_f32 v[12:13], v[12:13], v[16:17], v[18:19]
	v_cvt_pk_bf16_f32 v82, v30, v31
	v_cvt_pk_bf16_f32 v83, v32, v33
	v_cvt_pk_bf16_f32 v84, v14, v15
	v_cvt_pk_bf16_f32 v85, v12, v13
	v_cvt_pk_bf16_f32 v86, v26, v27
	v_cvt_pk_bf16_f32 v87, v28, v29
	v_cvt_pk_bf16_f32 v88, v10, v11
	v_cvt_pk_bf16_f32 v89, v20, v21
	v_mov_b32_e32 v10, v2
	v_mov_b32_e32 v11, v2
	v_mov_b32_e32 v12, v2
	v_mov_b32_e32 v13, v2
	v_mov_b32_e32 v14, v2
	v_mov_b32_e32 v15, v2
	v_mov_b32_e32 v16, v2
	v_mov_b32_e32 v17, v2
	v_mov_b32_e32 v18, v2
	v_mov_b32_e32 v19, v2
	v_mov_b32_e32 v20, v2
	v_mov_b32_e32 v21, v2
	v_mov_b32_e32 v22, v2
	v_mov_b32_e32 v23, v2
	v_mov_b32_e32 v24, v2
	v_mov_b32_e32 v25, v2
	v_mov_b32_e32 v26, v2
	v_mov_b32_e32 v27, v2
	v_mov_b32_e32 v28, v2
	v_mov_b32_e32 v29, v2
	v_mov_b32_e32 v30, v2
	v_mov_b32_e32 v31, v2
	v_mov_b32_e32 v32, v2
	v_mov_b32_e32 v33, v2
	v_mov_b32_e32 v34, v2
	v_mov_b32_e32 v35, v2
	v_mov_b32_e32 v40, v2
	v_mov_b32_e32 v41, v2
	v_mov_b32_e32 v42, v2
	v_mov_b32_e32 v43, v2
	v_mov_b32_e32 v46, v2
	v_mov_b32_e32 v47, v2
	v_mov_b32_e32 v48, v2
	v_mov_b32_e32 v49, v2
	s_waitcnt vmcnt(0)
	ds_write_b128 v201, v[230:233] offset:18432
	v_lshl_add_u64 v[114:115], v[114:115], 0, s[4:5]
	v_add_u32_e32 v246, v199, v200
	v_add_u32_e32 v127, 0x6c00, v203
	v_add_u32_e32 v129, 0x2400, v203
	v_mov_b32_e32 v118, s88
	v_mov_b32_e32 v119, s88
	v_mov_b32_e32 v120, s88
	v_mov_b32_e32 v121, s88
	v_add_u32_e32 v247, 0x2000, v246
	v_add_u32_e32 v0, 0x3000, v246
	v_add_u32_e32 v123, 0x6800, v246
	v_add_u32_e32 v125, 0x7800, v246
	s_waitcnt lgkmcnt(0)
	ds_read_b128 v[214:217], v204 offset:0
	ds_read_b128 v[218:221], v202 offset:0
	ds_read_b128 v[222:225], v204 offset:32
	ds_read_b128 v[226:229], v202 offset:32
	ds_read_b128 v[230:233], v204 offset:64
	ds_read_b128 v[234:237], v202 offset:64
	ds_read_b128 v[238:241], v204 offset:96
	ds_read_b128 v[242:245], v202 offset:96
	s_waitcnt lgkmcnt(7)
	v_mfma_f32_32x32x16_bf16 v[50:65], v[214:217], v[94:97], 0
	s_waitcnt lgkmcnt(6)
	v_mfma_f32_32x32x16_bf16 v[66:81], v[218:221], v[94:97], 0
	s_waitcnt lgkmcnt(5)
	v_mfma_f32_32x32x16_bf16 v[50:65], v[222:225], v[90:93], v[50:65]
	s_waitcnt lgkmcnt(4)
	v_mfma_f32_32x32x16_bf16 v[66:81], v[226:229], v[90:93], v[66:81]
	s_waitcnt lgkmcnt(3)
	v_mfma_f32_32x32x16_bf16 v[50:65], v[230:233], v[86:89], v[50:65]
	s_waitcnt lgkmcnt(2)
	v_mfma_f32_32x32x16_bf16 v[66:81], v[234:237], v[86:89], v[66:81]
	s_waitcnt lgkmcnt(1)
	v_mfma_f32_32x32x16_bf16 v[50:65], v[238:241], v[82:85], v[50:65]
	s_waitcnt lgkmcnt(0)
	v_mfma_f32_32x32x16_bf16 v[66:81], v[242:245], v[82:85], v[66:81]
	s_barrier
	s_nop 15
	v_exp_f32_e32 v50, v50
	v_exp_f32_e32 v51, v51
	v_exp_f32_e32 v52, v52
	v_exp_f32_e32 v53, v53
	v_exp_f32_e32 v54, v54
	v_exp_f32_e32 v55, v55
	v_exp_f32_e32 v56, v56
	v_exp_f32_e32 v57, v57
	v_cvt_pk_bf16_f32 v50, v50, v51
	v_cvt_pk_bf16_f32 v51, v52, v53
	v_cvt_pk_bf16_f32 v52, v54, v55
	v_cvt_pk_bf16_f32 v53, v56, v57
; #define LAS __attribute__((address_space(3)))
; template <bool TRACK> ...
;     ...
;             for (int d = 0; d < 4; ++d) { kf[2 * d] = *(const LAS bf16x8*)(Kbuf + (r32 * 72 + d * 16 + hi * 8) * 2); kf[2 * d + 1] = *(const LAS bf16x8*)(Kbuf + ((32 + r32) * 72 + d * 16 + hi * 8) * 2); }
;             __builtin_amdgcn_sched_barrier(0);
; #pragma unroll
;             for (int d = 0; d < 4; ++d) {
;                 s0 = __builtin_amdgcn_mfma_f32_32x32x16_bf16(kf[2 * d], qf[d], s0, 0, 0, 0);
;                 s1 = __builtin_amdgcn_mfma_f32_32x32x16_bf16(kf[2 * d + 1], qf[d], s1, 0, 0, 0);
;             }
; #pragma unroll
;             for (int kc = 0; kc < 2; ++kc) {
;                 const LAS unsigned char* vp0 = Vbuf + (r32 * 68 + kc * 16 + 4 * hi) * 2; const LAS unsigned char* vp1 = vp0 + 32 * 68 * 2;
;                 vq[4 * kc] = *(const LAS u32x2*)vp0; vq[4 * kc + 1] = *(const LAS u32x2*)(vp0 + 16); vq[4 * kc + 2] = *(const LAS u32x2*)vp1; vq[4 * kc + 3] = *(const LAS u32x2*)(vp1 + 16); }
;             __builtin_amdgcn_sched_barrier(0);
;             } else {
; #pragma unroll
;             for (int d = 0; d < 4; ++d) {
;                 const bf16x8 a0 = *(const LAS bf16x8*)(Kbuf + (r32 * 72 + d * 16 + hi * 8) * 2);
;                 const bf16x8 a1 = *(const LAS bf16x8*)(Kbuf + ((32 + r32) * 72 + d * 16 + hi * 8) * 2);
;                 s0 = __builtin_amdgcn_mfma_f32_32x32x16_bf16(a0, qf[d], s0, 0, 0, 0);
;                 s1 = __builtin_amdgcn_mfma_f32_32x32x16_bf16(a1, qf[d], s1, 0, 0, 0);
;             }
;             }
;             if (mt) { const int qpos = qstart + wave * 32 + r32;
; #pragma unroll
;                 for (int r = 0; r < 16; ++r) { const int d0 = qpos - (kpos0 + crow(r, hi)); if (d0 > 128 || d0 < -128) s0[r] = -INFINITY; const int d1 = d0 - 32; if (d1 > 128 || d1 < -128) s1[r] = -INFINITY; } }
;             if (TRACK) {
;             float mx = fmaxf(fmaxf(s0[0], s1[0]), s0[1]);
; #pragma unroll
;             for (int r = 1; r < 15; r += 2) mx = fmaxf(fmaxf(mx, s1[r]), fmaxf(fmaxf(s0[r + 1], s1[r + 1]), s0[r + 2 < 16 ? r + 2 : 15]));
;             mx = fmaxf(mx, s1[15]);
;             mx = fmaxf(mx, __shfl_xor(mx, 32));
;             if (__any(mx > ATT_THR)) {
;                 const float dl = fmaxf(mx, 0.f); m += dl; const float alpha = __builtin_amdgcn_exp2f(-dl); lsum *= alpha;
; #pragma unroll
.LBB0_167:
	global_load_dwordx4 v[98:101], v[114:115], off
	global_load_dwordx4 v[102:105], v[116:117], off
	ds_read_b128 v[106:109], v204 offset:18432
	ds_read_b128 v[110:113], v202 offset:18432
	ds_read_b128 v[158:161], v204 offset:18464
	ds_read2_b64 v[206:209], v247 offset0:128 offset1:130
	ds_read2_b64 v[210:213], v0 offset0:160 offset1:162
	v_lshl_add_u64 v[114:115], v[114:115], 0, s[4:5]
	v_lshl_add_u64 v[116:117], v[116:117], 0, s[38:39]
	s_waitcnt lgkmcnt(4)
	v_mfma_f32_32x32x16_bf16 v[214:229], v[106:109], v[94:97], 0
	ds_read_b128 v[106:109], v202 offset:18464
	v_exp_f32_e32 v58, v58
	v_exp_f32_e32 v59, v59
	v_exp_f32_e32 v60, v60
	s_waitcnt lgkmcnt(4)
	v_mfma_f32_32x32x16_bf16 v[230:245], v[110:113], v[94:97], 0
	ds_read_b128 v[110:113], v204 offset:18496
	v_exp_f32_e32 v61, v61
	v_exp_f32_e32 v62, v62
	v_exp_f32_e32 v63, v63
	s_waitcnt lgkmcnt(4)
	v_mfma_f32_32x32x16_bf16 v[214:229], v[158:161], v[90:93], v[214:229]
	ds_read_b128 v[158:161], v202 offset:18496
	v_exp_f32_e32 v64, v64
	v_exp_f32_e32 v65, v65
	v_cvt_pk_bf16_f32 v54, v58, v59
	s_waitcnt lgkmcnt(2)
	v_mfma_f32_32x32x16_bf16 v[230:245], v[106:109], v[90:93], v[230:245]
	ds_read_b128 v[106:109], v204 offset:18528
	v_cvt_pk_bf16_f32 v55, v60, v61
	v_cvt_pk_bf16_f32 v56, v62, v63
	v_cvt_pk_bf16_f32 v57, v64, v65
	s_waitcnt lgkmcnt(2)
	v_mfma_f32_32x32x16_bf16 v[214:229], v[110:113], v[86:89], v[214:229]
	ds_read_b128 v[110:113], v202 offset:18528
	v_exp_f32_e32 v66, v66
	v_exp_f32_e32 v67, v67
	v_exp_f32_e32 v68, v68
	s_waitcnt lgkmcnt(2)
	v_mfma_f32_32x32x16_bf16 v[230:245], v[158:161], v[86:89], v[230:245]
	v_exp_f32_e32 v69, v69
	v_exp_f32_e32 v70, v70
	v_exp_f32_e32 v71, v71
	s_waitcnt lgkmcnt(1)
	v_mfma_f32_32x32x16_bf16 v[214:229], v[106:109], v[82:85], v[214:229]
	v_exp_f32_e32 v72, v72
	v_exp_f32_e32 v73, v73
	v_cvt_pk_bf16_f32 v66, v66, v67
	s_waitcnt lgkmcnt(0)
	v_mfma_f32_32x32x16_bf16 v[230:245], v[110:113], v[82:85], v[230:245]
	v_cvt_pk_bf16_f32 v67, v68, v69
	v_cvt_pk_bf16_f32 v68, v70, v71
	v_cvt_pk_bf16_f32 v69, v72, v73
	v_mfma_f32_32x32x16_bf16 v[2:17], v[206:209], v[50:53], v[2:17]
	ds_read2_b64 v[206:209], v247 offset0:132 offset1:134
	v_exp_f32_e32 v74, v74
	v_exp_f32_e32 v75, v75
	v_exp_f32_e32 v76, v76
	v_mfma_f32_32x32x16_bf16 v[18:33], v[210:213], v[50:53], v[18:33]
	ds_read2_b64 v[210:213], v0 offset0:164 offset1:166
	v_exp_f32_e32 v77, v77
	v_exp_f32_e32 v78, v78
	v_exp_f32_e32 v79, v79
	v_mfma_f32_32x32x16_bf16 v[34:49], v[118:121], v[50:53], v[34:49]
	v_exp_f32_e32 v80, v80
	v_exp_f32_e32 v81, v81
	v_cvt_pk_bf16_f32 v70, v74, v75
	s_waitcnt lgkmcnt(1)
	v_mfma_f32_32x32x16_bf16 v[2:17], v[206:209], v[54:57], v[2:17]
	ds_read2_b64 v[206:209], v247 offset0:136 offset1:138
	v_cvt_pk_bf16_f32 v71, v76, v77
	v_cvt_pk_bf16_f32 v72, v78, v79
	v_cvt_pk_bf16_f32 v73, v80, v81
	s_waitcnt lgkmcnt(1)
	v_mfma_f32_32x32x16_bf16 v[18:33], v[210:213], v[54:57], v[18:33]
	ds_read2_b64 v[210:213], v0 offset0:168 offset1:170
	v_mfma_f32_32x32x16_bf16 v[34:49], v[118:121], v[54:57], v[34:49]
	s_waitcnt vmcnt(1)
	ds_write_b128 v201, v[98:101] offset:0
	s_waitcnt vmcnt(0)
	ds_write2_b64 v127, v[102:103], v[104:105] offset1:1
	s_waitcnt lgkmcnt(3)
	v_mfma_f32_32x32x16_bf16 v[2:17], v[206:209], v[66:69], v[2:17]
	ds_read2_b64 v[206:209], v247 offset0:140 offset1:142
	v_exp_f32_e32 v214, v214
	v_exp_f32_e32 v215, v215
	s_waitcnt lgkmcnt(3)
	v_mfma_f32_32x32x16_bf16 v[18:33], v[210:213], v[66:69], v[18:33]
	ds_read2_b64 v[210:213], v0 offset0:172 offset1:174
	v_exp_f32_e32 v216, v216
	v_exp_f32_e32 v217, v217
	v_mfma_f32_32x32x16_bf16 v[34:49], v[118:121], v[66:69], v[34:49]
	v_exp_f32_e32 v218, v218
	v_exp_f32_e32 v219, v219
	s_waitcnt lgkmcnt(1)
	v_mfma_f32_32x32x16_bf16 v[2:17], v[206:209], v[70:73], v[2:17]
	v_exp_f32_e32 v220, v220
	v_exp_f32_e32 v221, v221
	s_waitcnt lgkmcnt(0)
	v_mfma_f32_32x32x16_bf16 v[18:33], v[210:213], v[70:73], v[18:33]
	v_cvt_pk_bf16_f32 v214, v214, v215
	v_cvt_pk_bf16_f32 v215, v216, v217
	v_mfma_f32_32x32x16_bf16 v[34:49], v[118:121], v[70:73], v[34:49]
	v_cvt_pk_bf16_f32 v216, v218, v219
	v_cvt_pk_bf16_f32 v217, v220, v221
	s_waitcnt lgkmcnt(0)
	s_barrier
	global_load_dwordx4 v[98:101], v[114:115], off
	global_load_dwordx4 v[102:105], v[116:117], off
	ds_read_b128 v[106:109], v204 offset:0
	ds_read_b128 v[110:113], v202 offset:0
	ds_read_b128 v[158:161], v204 offset:32
	ds_read2_b64 v[206:209], v123 offset0:128 offset1:130
	ds_read2_b64 v[210:213], v125 offset0:160 offset1:162
	v_lshl_add_u64 v[114:115], v[114:115], 0, s[4:5]
	v_lshl_add_u64 v[116:117], v[116:117], 0, s[38:39]
	s_waitcnt lgkmcnt(4)
	v_mfma_f32_32x32x16_bf16 v[50:65], v[106:109], v[94:97], 0
	ds_read_b128 v[106:109], v202 offset:32
	v_exp_f32_e32 v222, v222
	v_exp_f32_e32 v223, v223
	v_exp_f32_e32 v224, v224
	s_waitcnt lgkmcnt(4)
	v_mfma_f32_32x32x16_bf16 v[66:81], v[110:113], v[94:97], 0
	ds_read_b128 v[110:113], v204 offset:64
	v_exp_f32_e32 v225, v225
	v_exp_f32_e32 v226, v226
	v_exp_f32_e32 v227, v227
	s_waitcnt lgkmcnt(4)
	v_mfma_f32_32x32x16_bf16 v[50:65], v[158:161], v[90:93], v[50:65]
	ds_read_b128 v[158:161], v202 offset:64
	v_exp_f32_e32 v228, v228
	v_exp_f32_e32 v229, v229
	v_cvt_pk_bf16_f32 v218, v222, v223
	s_waitcnt lgkmcnt(2)
	v_mfma_f32_32x32x16_bf16 v[66:81], v[106:109], v[90:93], v[66:81]
	ds_read_b128 v[106:109], v204 offset:96
	v_cvt_pk_bf16_f32 v219, v224, v225
	v_cvt_pk_bf16_f32 v220, v226, v227
	v_cvt_pk_bf16_f32 v221, v228, v229
	s_waitcnt lgkmcnt(2)
	v_mfma_f32_32x32x16_bf16 v[50:65], v[110:113], v[86:89], v[50:65]
	ds_read_b128 v[110:113], v202 offset:96
	v_exp_f32_e32 v230, v230
	v_exp_f32_e32 v231, v231
	v_exp_f32_e32 v232, v232
	s_waitcnt lgkmcnt(2)
; #define LAS __attribute__((address_space(3)))
; template <bool TRACK> ...
;     ...
;             for (int d = 0; d < 4; ++d) { kf[2 * d] = *(const LAS bf16x8*)(Kbuf + (r32 * 72 + d * 16 + hi * 8) * 2); kf[2 * d + 1] = *(const LAS bf16x8*)(Kbuf + ((32 + r32) * 72 + d * 16 + hi * 8) * 2); }
;             __builtin_amdgcn_sched_barrier(0);
; #pragma unroll
;             for (int d = 0; d < 4; ++d) {
;                 s0 = __builtin_amdgcn_mfma_f32_32x32x16_bf16(kf[2 * d], qf[d], s0, 0, 0, 0);
;                 s1 = __builtin_amdgcn_mfma_f32_32x32x16_bf16(kf[2 * d + 1], qf[d], s1, 0, 0, 0);
;             }
; #pragma unroll
;             for (int kc = 0; kc < 2; ++kc) {
;                 const LAS unsigned char* vp0 = Vbuf + (r32 * 68 + kc * 16 + 4 * hi) * 2; const LAS unsigned char* vp1 = vp0 + 32 * 68 * 2;
;                 vq[4 * kc] = *(const LAS u32x2*)vp0; vq[4 * kc + 1] = *(const LAS u32x2*)(vp0 + 16); vq[4 * kc + 2] = *(const LAS u32x2*)vp1; vq[4 * kc + 3] = *(const LAS u32x2*)(vp1 + 16); }
;             __builtin_amdgcn_sched_barrier(0);
;             } else {
; #pragma unroll
;             for (int d = 0; d < 4; ++d) {
;                 const bf16x8 a0 = *(const LAS bf16x8*)(Kbuf + (r32 * 72 + d * 16 + hi * 8) * 2);
;                 const bf16x8 a1 = *(const LAS bf16x8*)(Kbuf + ((32 + r32) * 72 + d * 16 + hi * 8) * 2);
;                 s0 = __builtin_amdgcn_mfma_f32_32x32x16_bf16(a0, qf[d], s0, 0, 0, 0);
;                 s1 = __builtin_amdgcn_mfma_f32_32x32x16_bf16(a1, qf[d], s1, 0, 0, 0);
;             }
;             }
;             if (mt) { const int qpos = qstart + wave * 32 + r32;
; #pragma unroll
;                 for (int r = 0; r < 16; ++r) { const int d0 = qpos - (kpos0 + crow(r, hi)); if (d0 > 128 || d0 < -128) s0[r] = -INFINITY; const int d1 = d0 - 32; if (d1 > 128 || d1 < -128) s1[r] = -INFINITY; } }
;             if (TRACK) {
;             float mx = fmaxf(fmaxf(s0[0], s1[0]), s0[1]);
; #pragma unroll
;             for (int r = 1; r < 15; r += 2) mx = fmaxf(fmaxf(mx, s1[r]), fmaxf(fmaxf(s0[r + 1], s1[r + 1]), s0[r + 2 < 16 ? r + 2 : 15]));
;             mx = fmaxf(mx, s1[15]);
;             mx = fmaxf(mx, __shfl_xor(mx, 32));
;             if (__any(mx > ATT_THR)) {
;                 const float dl = fmaxf(mx, 0.f); m += dl; const float alpha = __builtin_amdgcn_exp2f(-dl); lsum *= alpha;
; #pragma unroll
	v_mfma_f32_32x32x16_bf16 v[66:81], v[158:161], v[86:89], v[66:81]
	v_exp_f32_e32 v233, v233
	v_exp_f32_e32 v234, v234
	v_exp_f32_e32 v235, v235
	s_waitcnt lgkmcnt(1)
	v_mfma_f32_32x32x16_bf16 v[50:65], v[106:109], v[82:85], v[50:65]
	v_exp_f32_e32 v236, v236
	v_exp_f32_e32 v237, v237
	v_cvt_pk_bf16_f32 v230, v230, v231
	s_waitcnt lgkmcnt(0)
	v_mfma_f32_32x32x16_bf16 v[66:81], v[110:113], v[82:85], v[66:81]
	v_cvt_pk_bf16_f32 v231, v232, v233
	v_cvt_pk_bf16_f32 v232, v234, v235
	v_cvt_pk_bf16_f32 v233, v236, v237
	v_mfma_f32_32x32x16_bf16 v[2:17], v[206:209], v[214:217], v[2:17]
	ds_read2_b64 v[206:209], v123 offset0:132 offset1:134
	v_exp_f32_e32 v238, v238
	v_exp_f32_e32 v239, v239
	v_exp_f32_e32 v240, v240
	v_mfma_f32_32x32x16_bf16 v[18:33], v[210:213], v[214:217], v[18:33]
	ds_read2_b64 v[210:213], v125 offset0:164 offset1:166
	v_exp_f32_e32 v241, v241
	v_exp_f32_e32 v242, v242
	v_exp_f32_e32 v243, v243
	v_mfma_f32_32x32x16_bf16 v[34:49], v[118:121], v[214:217], v[34:49]
	v_exp_f32_e32 v244, v244
	v_exp_f32_e32 v245, v245
	v_cvt_pk_bf16_f32 v234, v238, v239
	s_waitcnt lgkmcnt(1)
	v_mfma_f32_32x32x16_bf16 v[2:17], v[206:209], v[218:221], v[2:17]
	ds_read2_b64 v[206:209], v123 offset0:136 offset1:138
	v_cvt_pk_bf16_f32 v235, v240, v241
	v_cvt_pk_bf16_f32 v236, v242, v243
	v_cvt_pk_bf16_f32 v237, v244, v245
	s_waitcnt lgkmcnt(1)
	v_mfma_f32_32x32x16_bf16 v[18:33], v[210:213], v[218:221], v[18:33]
	ds_read2_b64 v[210:213], v125 offset0:168 offset1:170
	v_mfma_f32_32x32x16_bf16 v[34:49], v[118:121], v[218:221], v[34:49]
	s_waitcnt vmcnt(1)
	ds_write_b128 v201, v[98:101] offset:18432
	s_waitcnt vmcnt(0)
	ds_write2_b64 v129, v[102:103], v[104:105] offset1:1
	s_waitcnt lgkmcnt(3)
	v_mfma_f32_32x32x16_bf16 v[2:17], v[206:209], v[230:233], v[2:17]
	ds_read2_b64 v[206:209], v123 offset0:140 offset1:142
	v_exp_f32_e32 v50, v50
	v_exp_f32_e32 v51, v51
	s_waitcnt lgkmcnt(3)
	v_mfma_f32_32x32x16_bf16 v[18:33], v[210:213], v[230:233], v[18:33]
	ds_read2_b64 v[210:213], v125 offset0:172 offset1:174
	v_exp_f32_e32 v52, v52
	v_exp_f32_e32 v53, v53
	v_mfma_f32_32x32x16_bf16 v[34:49], v[118:121], v[230:233], v[34:49]
	v_exp_f32_e32 v54, v54
	v_exp_f32_e32 v55, v55
	s_waitcnt lgkmcnt(1)
	v_mfma_f32_32x32x16_bf16 v[2:17], v[206:209], v[234:237], v[2:17]
	v_exp_f32_e32 v56, v56
	v_exp_f32_e32 v57, v57
	s_waitcnt lgkmcnt(0)
	v_mfma_f32_32x32x16_bf16 v[18:33], v[210:213], v[234:237], v[18:33]
	v_cvt_pk_bf16_f32 v50, v50, v51
	v_cvt_pk_bf16_f32 v51, v52, v53
	v_mfma_f32_32x32x16_bf16 v[34:49], v[118:121], v[234:237], v[34:49]
	v_cvt_pk_bf16_f32 v52, v54, v55
	v_cvt_pk_bf16_f32 v53, v56, v57
	s_add_i32 s20, s20, 2
	s_cmp_lg_u32 s20, 36
	s_waitcnt lgkmcnt(0)
	s_barrier
	s_cbranch_scc1 .LBB0_167
	s_nop 15
	v_readlane_b32 s89, v248, 3
	v_div_scale_f32 v0, s[20:21], v34, v34, 1.0
	v_rcp_f32_e32 v35, v0
	s_waitcnt lgkmcnt(0)
	s_barrier
	v_fma_f32 v36, -v0, v35, 1.0
	v_fmac_f32_e32 v35, v36, v35
	v_div_scale_f32 v36, vcc, 1.0, v34, 1.0
	v_mul_f32_e32 v37, v36, v35
	v_fma_f32 v38, -v0, v37, v36
	v_fmac_f32_e32 v37, v38, v35
	v_fma_f32 v0, -v0, v37, v36
	v_div_fmas_f32 v0, v0, v35, v37
	v_div_fixup_f32 v0, v0, v34, 1.0
	s_nop 1
	v_mul_f32_e64 v2, v2, v0
	v_mul_f32_e64 v3, v3, v0
	v_pk_mul_f32 v[4:5], v[4:5], v[0:1] op_sel_hi:[1,0]
	v_add_u32_e32 v34, v198, v156
	ds_write_b128 v34, v[2:5] offset:40960
	v_pk_mul_f32 v[2:3], v[6:7], v[0:1] op_sel_hi:[1,0]
	v_pk_mul_f32 v[4:5], v[8:9], v[0:1] op_sel_hi:[1,0]
	ds_write_b128 v34, v[2:5] offset:40992
	v_pk_mul_f32 v[2:3], v[10:11], v[0:1] op_sel_hi:[1,0]
	v_pk_mul_f32 v[4:5], v[12:13], v[0:1] op_sel_hi:[1,0]
	ds_write_b128 v34, v[2:5] offset:41024
	v_pk_mul_f32 v[2:3], v[14:15], v[0:1] op_sel_hi:[1,0]
	v_pk_mul_f32 v[4:5], v[16:17], v[0:1] op_sel_hi:[1,0]
	ds_write_b128 v34, v[2:5] offset:41056
	v_pk_mul_f32 v[2:3], v[18:19], v[0:1] op_sel_hi:[1,0]
	v_pk_mul_f32 v[4:5], v[20:21], v[0:1] op_sel_hi:[1,0]
	ds_write_b128 v34, v[2:5] offset:41088
	v_pk_mul_f32 v[2:3], v[22:23], v[0:1] op_sel_hi:[1,0]
	v_pk_mul_f32 v[4:5], v[24:25], v[0:1] op_sel_hi:[1,0]
	ds_write_b128 v34, v[2:5] offset:41120
	v_pk_mul_f32 v[2:3], v[26:27], v[0:1] op_sel_hi:[1,0]
	v_pk_mul_f32 v[4:5], v[28:29], v[0:1] op_sel_hi:[1,0]
	ds_write_b128 v34, v[2:5] offset:41152
	v_pk_mul_f32 v[2:3], v[30:31], v[0:1] op_sel_hi:[1,0]
	v_pk_mul_f32 v[4:5], v[32:33], v[0:1] op_sel_hi:[1,0]
	ds_write_b128 v34, v[2:5] offset:41184
	v_add_u32_e32 v0, v192, v193
	ds_read_b128 v[6:9], v0 offset:40960
	ds_read_b128 v[2:5], v0 offset:40976
	global_load_dwordx4 v[10:13], v[154:155], off offset:1280
	s_waitcnt vmcnt(0)
	v_lshlrev_b32_e32 v14, 16, v10
	v_and_b32_e32 v15, 0xffff0000, v10
	v_mul_f32_e32 v10, 0xbfb8aa3b, v14
	v_exp_f32_e32 v10, v10
	s_nop 0
	v_add_f32_e32 v10, 1.0, v10
	v_rcp_f32_e32 v16, v10
	v_mul_f32_e32 v10, 0xbfb8aa3b, v15
	v_exp_f32_e32 v10, v10
	s_nop 0
	v_add_f32_e32 v10, 1.0, v10
	v_rcp_f32_e32 v17, v10
	v_lshlrev_b32_e32 v10, 16, v11
	v_and_b32_e32 v11, 0xffff0000, v11
	v_pk_mul_f32 v[14:15], v[16:17], v[14:15]
	s_waitcnt lgkmcnt(1)
	v_pk_mul_f32 v[6:7], v[6:7], v[14:15]
	s_nop 0
	v_cvt_pk_bf16_f32 v6, v6, v7
	v_mul_f32_e32 v7, 0xbfb8aa3b, v10
	v_exp_f32_e32 v7, v7
	s_nop 0
	v_add_f32_e32 v7, 1.0, v7
	v_rcp_f32_e32 v14, v7
	v_mul_f32_e32 v7, 0xbfb8aa3b, v11
	v_exp_f32_e32 v7, v7
	s_nop 0
	v_add_f32_e32 v7, 1.0, v7
	v_rcp_f32_e32 v15, v7
	s_nop 0
	v_pk_mul_f32 v[10:11], v[14:15], v[10:11]
	s_nop 0
	v_pk_mul_f32 v[8:9], v[8:9], v[10:11]
	s_nop 0
	v_cvt_pk_bf16_f32 v7, v8, v9
	v_lshlrev_b32_e32 v8, 16, v12
	v_and_b32_e32 v9, 0xffff0000, v12
	v_mul_f32_e32 v10, 0xbfb8aa3b, v8
	v_mul_f32_e32 v11, 0xbfb8aa3b, v9
	v_exp_f32_e32 v10, v10
	v_exp_f32_e32 v11, v11
	v_add_f32_e32 v10, 1.0, v10
	v_add_f32_e32 v11, 1.0, v11
	v_rcp_f32_e32 v10, v10
	v_rcp_f32_e32 v11, v11
	s_nop 0
	v_pk_mul_f32 v[8:9], v[10:11], v[8:9]
	s_waitcnt lgkmcnt(0)
; #define LAS __attribute__((address_space(3)))
; __device__ __forceinline__ unsigned pk2(float lo, float hi) { f32x2_t v = {lo, hi}; bf16x2_t b = __builtin_convertvector(v, bf16x2_t); return __builtin_bit_cast(unsigned, b); }
; __device__ __forceinline__ float silu_f(float v) { return v * __builtin_amdgcn_rcpf(1.0f + __expf(-v)); }
; template <bool TRACK> ...
;     ...
;         const int pc = lane & 7;
; #pragma unroll
;         for (int i = 0; i < 4; ++i) { const int rw = i * 8 + (lane >> 3), row = wave * 32 + rw;
;             const f32x4 oa = *(const LAS f32x4*)(scr + rw * 272 + pc * 32), ob = *(const LAS f32x4*)(scr + rw * 272 + pc * 32 + 16);
;             float gv[8]; unpack8(*(const u32x4*)(gate + (size_t)row * INW + 8 * pc), gv);
;             u32x4 w; w.x = pk2(oa.x * silu_f(gv[0]), oa.y * silu_f(gv[1])); w.y = pk2(oa.z * silu_f(gv[2]), oa.w * silu_f(gv[3]));
;             w.z = pk2(ob.x * silu_f(gv[4]), ob.y * silu_f(gv[5])); w.w = pk2(ob.z * silu_f(gv[6]), ob.w * silu_f(gv[7]));
;             *(u32x4*)(outp + (size_t)row * DM + 8 * pc) = w; }
	v_pk_mul_f32 v[2:3], v[2:3], v[8:9]
	s_nop 0
	v_cvt_pk_bf16_f32 v8, v2, v3
	v_lshlrev_b32_e32 v2, 16, v13
	v_mul_f32_e32 v9, 0xbfb8aa3b, v2
	v_exp_f32_e32 v9, v9
	v_and_b32_e32 v3, 0xffff0000, v13
	v_add_f32_e32 v9, 1.0, v9
	v_rcp_f32_e32 v10, v9
	v_mul_f32_e32 v9, 0xbfb8aa3b, v3
	v_exp_f32_e32 v9, v9
	s_nop 0
	v_add_f32_e32 v9, 1.0, v9
	v_rcp_f32_e32 v11, v9
	s_nop 0
	v_pk_mul_f32 v[2:3], v[10:11], v[2:3]
	s_nop 0
	v_pk_mul_f32 v[2:3], v[4:5], v[2:3]
	s_nop 0
	v_cvt_pk_bf16_f32 v9, v2, v3
	global_store_dwordx4 v[152:153], v[6:9], off
	ds_read_b128 v[6:9], v0 offset:43136
	ds_read_b128 v[2:5], v0 offset:43152
	global_load_dwordx4 v[10:13], v[150:151], off offset:1280
	s_waitcnt vmcnt(0)
	v_lshlrev_b32_e32 v14, 16, v10
	v_and_b32_e32 v15, 0xffff0000, v10
	v_mul_f32_e32 v10, 0xbfb8aa3b, v14
	v_exp_f32_e32 v10, v10
	s_nop 0
	v_add_f32_e32 v10, 1.0, v10
	v_rcp_f32_e32 v16, v10
	v_mul_f32_e32 v10, 0xbfb8aa3b, v15
	v_exp_f32_e32 v10, v10
	s_nop 0
	v_add_f32_e32 v10, 1.0, v10
	v_rcp_f32_e32 v17, v10
	v_lshlrev_b32_e32 v10, 16, v11
	v_and_b32_e32 v11, 0xffff0000, v11
	v_pk_mul_f32 v[14:15], v[16:17], v[14:15]
	s_waitcnt lgkmcnt(1)
	v_pk_mul_f32 v[6:7], v[6:7], v[14:15]
	s_nop 0
	v_cvt_pk_bf16_f32 v6, v6, v7
	v_mul_f32_e32 v7, 0xbfb8aa3b, v10
	v_exp_f32_e32 v7, v7
	s_nop 0
	v_add_f32_e32 v7, 1.0, v7
	v_rcp_f32_e32 v14, v7
	v_mul_f32_e32 v7, 0xbfb8aa3b, v11
	v_exp_f32_e32 v7, v7
	s_nop 0
	v_add_f32_e32 v7, 1.0, v7
	v_rcp_f32_e32 v15, v7
	s_nop 0
	v_pk_mul_f32 v[10:11], v[14:15], v[10:11]
	s_nop 0
	v_pk_mul_f32 v[8:9], v[8:9], v[10:11]
	s_nop 0
	v_cvt_pk_bf16_f32 v7, v8, v9
	v_lshlrev_b32_e32 v8, 16, v12
	v_and_b32_e32 v9, 0xffff0000, v12
	v_mul_f32_e32 v10, 0xbfb8aa3b, v8
	v_mul_f32_e32 v11, 0xbfb8aa3b, v9
	v_exp_f32_e32 v10, v10
	v_exp_f32_e32 v11, v11
	v_add_f32_e32 v10, 1.0, v10
	v_add_f32_e32 v11, 1.0, v11
	v_rcp_f32_e32 v10, v10
	v_rcp_f32_e32 v11, v11
	s_nop 0
	v_pk_mul_f32 v[8:9], v[10:11], v[8:9]
	s_waitcnt lgkmcnt(0)
	v_pk_mul_f32 v[2:3], v[2:3], v[8:9]
	s_nop 0
	v_cvt_pk_bf16_f32 v8, v2, v3
	v_lshlrev_b32_e32 v2, 16, v13
	v_mul_f32_e32 v9, 0xbfb8aa3b, v2
	v_exp_f32_e32 v9, v9
	v_and_b32_e32 v3, 0xffff0000, v13
	v_add_f32_e32 v9, 1.0, v9
	v_rcp_f32_e32 v10, v9
	v_mul_f32_e32 v9, 0xbfb8aa3b, v3
	v_exp_f32_e32 v9, v9
	s_nop 0
	v_add_f32_e32 v9, 1.0, v9
	v_rcp_f32_e32 v11, v9
	s_nop 0
	v_pk_mul_f32 v[2:3], v[10:11], v[2:3]
	s_nop 0
	v_pk_mul_f32 v[2:3], v[4:5], v[2:3]
	s_nop 0
	v_cvt_pk_bf16_f32 v9, v2, v3
	global_store_dwordx4 v[144:145], v[6:9], off
	ds_read_b128 v[6:9], v0 offset:45312
	ds_read_b128 v[2:5], v0 offset:45328
	global_load_dwordx4 v[10:13], v[142:143], off offset:1280
	s_waitcnt vmcnt(0)
	v_lshlrev_b32_e32 v14, 16, v10
	v_and_b32_e32 v15, 0xffff0000, v10
	v_mul_f32_e32 v10, 0xbfb8aa3b, v14
	v_exp_f32_e32 v10, v10
	s_nop 0
	v_add_f32_e32 v10, 1.0, v10
	v_rcp_f32_e32 v16, v10
	v_mul_f32_e32 v10, 0xbfb8aa3b, v15
	v_exp_f32_e32 v10, v10
	s_nop 0
	v_add_f32_e32 v10, 1.0, v10
	v_rcp_f32_e32 v17, v10
	v_lshlrev_b32_e32 v10, 16, v11
	v_and_b32_e32 v11, 0xffff0000, v11
	v_pk_mul_f32 v[14:15], v[16:17], v[14:15]
	s_waitcnt lgkmcnt(1)
	v_pk_mul_f32 v[6:7], v[6:7], v[14:15]
	s_nop 0
	v_cvt_pk_bf16_f32 v6, v6, v7
	v_mul_f32_e32 v7, 0xbfb8aa3b, v10
	v_exp_f32_e32 v7, v7
	s_nop 0
	v_add_f32_e32 v7, 1.0, v7
	v_rcp_f32_e32 v14, v7
	v_mul_f32_e32 v7, 0xbfb8aa3b, v11
	v_exp_f32_e32 v7, v7
	s_nop 0
	v_add_f32_e32 v7, 1.0, v7
	v_rcp_f32_e32 v15, v7
	s_nop 0
	v_pk_mul_f32 v[10:11], v[14:15], v[10:11]
	s_nop 0
	v_pk_mul_f32 v[8:9], v[8:9], v[10:11]
	s_nop 0
	v_cvt_pk_bf16_f32 v7, v8, v9
	v_lshlrev_b32_e32 v8, 16, v12
	v_and_b32_e32 v9, 0xffff0000, v12
	v_mul_f32_e32 v10, 0xbfb8aa3b, v8
	v_mul_f32_e32 v11, 0xbfb8aa3b, v9
	v_exp_f32_e32 v10, v10
	v_exp_f32_e32 v11, v11
	v_add_f32_e32 v10, 1.0, v10
	v_add_f32_e32 v11, 1.0, v11
	v_rcp_f32_e32 v10, v10
	v_rcp_f32_e32 v11, v11
	s_nop 0
	v_pk_mul_f32 v[8:9], v[10:11], v[8:9]
	s_waitcnt lgkmcnt(0)
	v_pk_mul_f32 v[2:3], v[2:3], v[8:9]
	s_nop 0
	v_cvt_pk_bf16_f32 v8, v2, v3
	v_lshlrev_b32_e32 v2, 16, v13
	v_mul_f32_e32 v9, 0xbfb8aa3b, v2
	v_exp_f32_e32 v9, v9
	v_and_b32_e32 v3, 0xffff0000, v13
	v_add_f32_e32 v9, 1.0, v9
	v_rcp_f32_e32 v10, v9
	v_mul_f32_e32 v9, 0xbfb8aa3b, v3
	v_exp_f32_e32 v9, v9
	s_nop 0
	v_add_f32_e32 v9, 1.0, v9
	v_rcp_f32_e32 v11, v9
	s_nop 0
	v_pk_mul_f32 v[2:3], v[10:11], v[2:3]
	s_nop 0
	v_pk_mul_f32 v[2:3], v[4:5], v[2:3]
	s_nop 0
	v_cvt_pk_bf16_f32 v9, v2, v3
	global_store_dwordx4 v[140:141], v[6:9], off
	ds_read_b128 v[6:9], v0 offset:47488
	ds_read_b128 v[2:5], v0 offset:47504
	global_load_dwordx4 v[10:13], v[138:139], off offset:1280
	s_waitcnt vmcnt(0)
	v_lshlrev_b32_e32 v14, 16, v10
	v_mul_f32_e32 v0, 0xbfb8aa3b, v14
	v_exp_f32_e32 v0, v0
	v_and_b32_e32 v15, 0xffff0000, v10
	v_lshlrev_b32_e32 v10, 16, v11
	v_and_b32_e32 v11, 0xffff0000, v11
	v_add_f32_e32 v0, 1.0, v0
	v_rcp_f32_e32 v16, v0
	v_mul_f32_e32 v0, 0xbfb8aa3b, v15
	v_exp_f32_e32 v0, v0
	s_nop 0
	v_add_f32_e32 v0, 1.0, v0
	v_rcp_f32_e32 v17, v0
	v_mul_f32_e32 v0, 0xbfb8aa3b, v10
	v_exp_f32_e32 v0, v0
	v_pk_mul_f32 v[14:15], v[16:17], v[14:15]
	s_waitcnt lgkmcnt(1)
	v_pk_mul_f32 v[6:7], v[6:7], v[14:15]
	v_add_f32_e32 v0, 1.0, v0
	v_rcp_f32_e32 v14, v0
	v_mul_f32_e32 v0, 0xbfb8aa3b, v11
	v_exp_f32_e32 v0, v0
	v_cvt_pk_bf16_f32 v6, v6, v7
	v_add_f32_e32 v0, 1.0, v0
	v_rcp_f32_e32 v15, v0
	s_nop 0
	v_pk_mul_f32 v[10:11], v[14:15], v[10:11]
	s_nop 0
	v_pk_mul_f32 v[8:9], v[8:9], v[10:11]
	s_nop 0
	v_cvt_pk_bf16_f32 v7, v8, v9
	v_lshlrev_b32_e32 v8, 16, v12
	v_mul_f32_e32 v0, 0xbfb8aa3b, v8
	v_exp_f32_e32 v0, v0
	v_and_b32_e32 v9, 0xffff0000, v12
	v_add_f32_e32 v0, 1.0, v0
	v_rcp_f32_e32 v10, v0
	v_mul_f32_e32 v0, 0xbfb8aa3b, v9
	v_exp_f32_e32 v0, v0
	s_nop 0
	v_add_f32_e32 v0, 1.0, v0
	v_rcp_f32_e32 v11, v0
	s_nop 0
	v_pk_mul_f32 v[8:9], v[10:11], v[8:9]
	s_waitcnt lgkmcnt(0)
	v_pk_mul_f32 v[2:3], v[2:3], v[8:9]
	s_nop 0
	v_cvt_pk_bf16_f32 v8, v2, v3
	v_lshlrev_b32_e32 v2, 16, v13
	v_mul_f32_e32 v0, 0xbfb8aa3b, v2
	v_exp_f32_e32 v0, v0
	v_and_b32_e32 v3, 0xffff0000, v13
	v_add_f32_e32 v0, 1.0, v0
	v_rcp_f32_e32 v10, v0
	v_mul_f32_e32 v0, 0xbfb8aa3b, v3
	v_exp_f32_e32 v0, v0
	s_nop 0
	v_add_f32_e32 v0, 1.0, v0
	v_rcp_f32_e32 v11, v0
	s_nop 0
	v_pk_mul_f32 v[2:3], v[10:11], v[2:3]
	s_nop 0
	v_pk_mul_f32 v[2:3], v[4:5], v[2:3]
	s_nop 0
	v_cvt_pk_bf16_f32 v9, v2, v3
	global_store_dwordx4 v[136:137], v[6:9], off
